# MLA: next-tile staging writes moved from the head of S2 into S1 behind the 18th MFMA; odd S1 head requests 4 K fragments
# speedup vs baseline: 1.1172x; 1.0133x over previous
; __device__ __forceinline__ void mla_softmax_rel_kp(f32x16& p0, f32x16& p1, f32x16& negm, bool first, float& l_reg, float& alpha, bf16x8& pa0, bf16x8& pa1, bf16x8& pa2, bf16x8& pa3) {
;     ...
;         for (int r = 0; r < 16; ++r) { negm[r] = nm; p0[r] -= d; p1[r] -= d; }
;     }
; #pragma unroll
;     for (int r = 0; r < 16; ++r) { p0[r] = __builtin_amdgcn_exp2f(p0[r]); p1[r] = __builtin_amdgcn_exp2f(p1[r]); }
;     float ps = 0.f;
; #pragma unroll
;     for (int r = 0; r < 16; ++r) ps += p0[r];
; #pragma unroll
;     for (int r = 0; r < 16; ++r) ps += p1[r];
;     { auto rr = __builtin_amdgcn_permlane32_swap(__float_as_uint(ps), __float_as_uint(ps), false, false); ps = __uint_as_float(rr[0]) + __uint_as_float(rr[1]); }
;     l_reg = l_reg * alpha + ps;
; __device__ __forceinline__ void pv_both_kp(f32x16& o0, f32x16& o1, int vb, bf16x8 pa0, bf16x8 pa1, bf16x8 pa2, bf16x8 pa3) {
;     ...
;     o1 = __builtin_amdgcn_mfma_f32_32x32x16_bf16(pa0, PK(m0, n0), o1, 0, 0, 0);
;     o1 = __builtin_amdgcn_mfma_f32_32x32x16_bf16(pa1, PK(m1, n1), o1, 0, 0, 0);
;     o1 = __builtin_amdgcn_mfma_f32_32x32x16_bf16(pa2, PK(m2, n2), o1, 0, 0, 0);
;     o1 = __builtin_amdgcn_mfma_f32_32x32x16_bf16(pa3, PK(m3, n3), o1, 0, 0, 0);
.Lmla_nobar4:
	v_mfma_f32_32x32x16_bf16 v[16:31], v[60:63], v[206:209], v[16:31]
	v_mfma_f32_32x32x16_bf16 v[16:31], v[56:59], v[150:153], v[16:31]
	s_cmp_lg_u64 s[44:45], 0
	s_cbranch_scc0 .Lmla_w1_tail
	s_waitcnt vmcnt(3)
	ds_write_b128 v196, v[120:123]
	ds_write_b128 v197, v[128:131] offset:26624
	s_cmp_lg_u32 s8, 0
	s_cbranch_scc0 .LBB0_975
	ds_write_b128 v238, v[124:127] offset:128
.LBB0_975:
	v_mfma_f32_32x32x16_bf16 v[16:31], v[52:55], v[210:213], v[16:31]
	v_mfma_f32_32x32x16_bf16 v[16:31], v[48:51], v[214:217], v[16:31]
	v_exp_f32_e32 v218, v64
	v_exp_f32_e32 v219, v65
	v_exp_f32_e32 v220, v66
	v_exp_f32_e32 v221, v67
	v_add_f32_e32 v173, v218, v220
	v_exp_f32_e32 v222, v68
	v_add_f32_e32 v174, v219, v221
	v_exp_f32_e32 v223, v69
	v_add_f32_e32 v173, v222, v173
	v_exp_f32_e32 v224, v70
	v_add_f32_e32 v174, v223, v174
	v_exp_f32_e32 v225, v71
	v_add_f32_e32 v173, v224, v173
	v_exp_f32_e32 v226, v72
	v_add_f32_e32 v174, v225, v174
	v_exp_f32_e32 v227, v73
	v_add_f32_e32 v173, v226, v173
	v_exp_f32_e32 v228, v74
	v_add_f32_e32 v174, v227, v174
	v_exp_f32_e32 v229, v75
	v_add_f32_e32 v173, v228, v173
	v_exp_f32_e32 v230, v76
	v_add_f32_e32 v174, v229, v174
	v_exp_f32_e32 v231, v77
	v_add_f32_e32 v173, v230, v173
	v_exp_f32_e32 v232, v78
	v_add_f32_e32 v174, v231, v174
	v_exp_f32_e32 v233, v79
	v_add_f32_e32 v173, v232, v173
	v_exp_f32_e32 v234, v80
	v_add_f32_e32 v174, v233, v174
	v_exp_f32_e32 v240, v81
	v_add_f32_e32 v173, v234, v173
	v_exp_f32_e32 v241, v82
	v_add_f32_e32 v174, v240, v174
	v_exp_f32_e32 v242, v83
	v_add_f32_e32 v173, v241, v173
	v_exp_f32_e32 v243, v84
	v_add_f32_e32 v174, v242, v174
	v_exp_f32_e32 v244, v85
	v_add_f32_e32 v173, v243, v173
	v_exp_f32_e32 v245, v86
	v_add_f32_e32 v174, v244, v174
	v_exp_f32_e32 v246, v87
	v_add_f32_e32 v173, v245, v173
	v_exp_f32_e32 v247, v88
	v_add_f32_e32 v174, v246, v174
	v_exp_f32_e32 v248, v89
	v_add_f32_e32 v173, v247, v173
	v_exp_f32_e32 v249, v90
	v_add_f32_e32 v174, v248, v174
	v_exp_f32_e32 v250, v91
	v_add_f32_e32 v173, v249, v173
	v_exp_f32_e32 v251, v92
	v_add_f32_e32 v174, v250, v174
	v_exp_f32_e32 v252, v93
	v_add_f32_e32 v173, v251, v173
	v_exp_f32_e32 v253, v94
	v_add_f32_e32 v174, v252, v174
	v_exp_f32_e32 v172, v95
	v_add_f32_e32 v173, v253, v173
	v_add_f32_e32 v174, v172, v174
	v_add_f32_e32 v173, v173, v174
	v_cmp_ge_f32_e32 vcc, 0x47800000, v173
	s_cmp_eq_u64 vcc, exec
	s_cbranch_scc0 .LBB0_995
	v_add_f32_e32 v236, v236, v173

; __device__ __forceinline__ unsigned cvt_pk_bf16(float lo, float hi) { unsigned r; asm volatile("v_cvt_pk_bf16_f32 %0, %1, %2" : "=v"(r) : "v"(lo), "v"(hi)); return r; }
; __device__ __forceinline__ bf16x8 pack8(const f32x16& p, int base) {
;     u32x4 w = {cvt_pk_bf16(p[base + 0], p[base + 1]), cvt_pk_bf16(p[base + 2], p[base + 3]), cvt_pk_bf16(p[base + 4], p[base + 5]), cvt_pk_bf16(p[base + 6], p[base + 7])};
;     return *reinterpret_cast<bf16x8*>(&w);
; }
.Lmla_nobar5:
	ds_read_b128 v[168:171], v157 offset:13312
	ds_read_b128 v[162:165], v157 offset:19968
	ds_read_b128 v[146:149], v157 offset:13344
	ds_read_b128 v[150:153], v157 offset:20000
	v_cvt_pk_bf16_f32 v87, v245, v246
	v_cvt_pk_bf16_f32 v86, v243, v244
	v_cvt_pk_bf16_f32 v85, v241, v242
	v_cvt_pk_bf16_f32 v84, v234, v240
	v_cvt_pk_bf16_f32 v82, v251, v252
	v_cvt_pk_bf16_f32 v83, v253, v172
	v_cvt_pk_bf16_f32 v80, v247, v248
	v_cvt_pk_bf16_f32 v81, v249, v250
	v_cvt_pk_bf16_f32 v92, v218, v219
	v_cvt_pk_bf16_f32 v93, v220, v221
	v_cvt_pk_bf16_f32 v94, v222, v223
	v_cvt_pk_bf16_f32 v95, v224, v225
	v_cvt_pk_bf16_f32 v88, v226, v227
	v_cvt_pk_bf16_f32 v89, v228, v229
	v_cvt_pk_bf16_f32 v90, v230, v231
	v_cvt_pk_bf16_f32 v91, v232, v233
	s_add_u32 s60, s60, 0x20000
	s_addc_u32 s61, s61, 0
	s_add_u32 s62, s62, 0x20000
	s_addc_u32 s63, s63, 0
	s_add_u32 s64, s64, 0x1000
	s_addc_u32 s65, s65, 0
	s_add_i32 s47, s47, 3
	s_cmp_ge_i32 s47, s54
	s_cbranch_scc1 .LBB0_983
	global_load_dwordx4 v[120:123], v166, s[60:61]
	global_load_dwordx4 v[124:127], v167, s[64:65]

; __device__ __forceinline__ void mla_qkt_neg(f32x16& p0, f32x16& p1, const f32x16& negm, const unsigned char* Kb, const bf16x8* qr, int r32, int hi) {
; #pragma unroll
;     for (int d0 = 0; d0 < 6; ++d0) { const int cb = (d0 * 16 + hi * 8) * 2;
;         const bf16x8 b0 = *(const bf16x8*)(Kb + r32 * KSTR + cb), b1 = *(const bf16x8*)(Kb + (32 + r32) * KSTR + cb);
;         if (d0 == 0) { p0 = __builtin_amdgcn_mfma_f32_32x32x16_bf16(b0, qr[0], negm, 0, 0, 0); p1 = __builtin_amdgcn_mfma_f32_32x32x16_bf16(b1, qr[0], negm, 0, 0, 0); }
;         else { p0 = __builtin_amdgcn_mfma_f32_32x32x16_bf16(b0, qr[d0], p0, 0, 0, 0); p1 = __builtin_amdgcn_mfma_f32_32x32x16_bf16(b1, qr[d0], p1, 0, 0, 0); } }
; }
; __device__ __forceinline__ void pv_both_kp(f32x16& o0, f32x16& o1, int vb, bf16x8 pa0, bf16x8 pa1, bf16x8 pa2, bf16x8 pa3) {
;     const s16x4 l0 = tr_read<v_rd_off_kp(0, 0, 0)>(vb), h0 = tr_read<v_rd_off_kp(0, 0, 1)>(vb), l1 = tr_read<v_rd_off_kp(0, 1, 0)>(vb), h1 = tr_read<v_rd_off_kp(0, 1, 1)>(vb);
;     const s16x4 l2 = tr_read<v_rd_off_kp(0, 2, 0)>(vb), h2 = tr_read<v_rd_off_kp(0, 2, 1)>(vb), l3 = tr_read<v_rd_off_kp(0, 3, 0)>(vb), h3 = tr_read<v_rd_off_kp(0, 3, 1)>(vb);
;     const s16x4 m0 = tr_read<v_rd_off_kp(1, 0, 0)>(vb), n0 = tr_read<v_rd_off_kp(1, 0, 1)>(vb), m1 = tr_read<v_rd_off_kp(1, 1, 0)>(vb), n1 = tr_read<v_rd_off_kp(1, 1, 1)>(vb);
;     const s16x4 m2 = tr_read<v_rd_off_kp(1, 2, 0)>(vb), n2 = tr_read<v_rd_off_kp(1, 2, 1)>(vb), m3 = tr_read<v_rd_off_kp(1, 3, 0)>(vb), n3 = tr_read<v_rd_off_kp(1, 3, 1)>(vb);
;     asm volatile("s_waitcnt lgkmcnt(8)" ::: "memory"); __builtin_amdgcn_sched_barrier(0);
;     ...
;     o0 = __builtin_amdgcn_mfma_f32_32x32x16_bf16(pa0, PK(l0, h0), o0, 0, 0, 0);
;     o0 = __builtin_amdgcn_mfma_f32_32x32x16_bf16(pa1, PK(l1, h1), o0, 0, 0, 0);
;     o0 = __builtin_amdgcn_mfma_f32_32x32x16_bf16(pa2, PK(l2, h2), o0, 0, 0, 0);
;     o0 = __builtin_amdgcn_mfma_f32_32x32x16_bf16(pa3, PK(l3, h3), o0, 0, 0, 0);
;     asm volatile("s_waitcnt lgkmcnt(0)" ::: "memory"); __builtin_amdgcn_sched_barrier(0);
;     o1 = __builtin_amdgcn_mfma_f32_32x32x16_bf16(pa0, PK(m0, n0), o1, 0, 0, 0);
;     o1 = __builtin_amdgcn_mfma_f32_32x32x16_bf16(pa1, PK(m1, n1), o1, 0, 0, 0);
;     o1 = __builtin_amdgcn_mfma_f32_32x32x16_bf16(pa2, PK(m2, n2), o1, 0, 0, 0);
;     o1 = __builtin_amdgcn_mfma_f32_32x32x16_bf16(pa3, PK(m3, n3), o1, 0, 0, 0);
;     ...
; }
.LBB0_985:
	s_waitcnt lgkmcnt(3)
	v_mfma_f32_32x32x16_bf16 v[64:79], v[168:171], v[96:99], v[32:47]
	s_waitcnt lgkmcnt(2)
	v_mfma_f32_32x32x16_bf16 v[48:63], v[162:165], v[96:99], v[32:47]
	s_waitcnt lgkmcnt(1)
	v_mfma_f32_32x32x16_bf16 v[64:79], v[146:149], v[100:103], v[64:79]
	ds_read_b128 v[168:171], v157 offset:13376
	ds_read_b128 v[162:165], v157 offset:20032
	s_waitcnt lgkmcnt(2)
	v_mfma_f32_32x32x16_bf16 v[48:63], v[150:153], v[100:103], v[48:63]
	s_waitcnt lgkmcnt(1)
	v_mfma_f32_32x32x16_bf16 v[64:79], v[168:171], v[104:107], v[64:79]
	ds_read_b128 v[146:149], v157 offset:13408
	ds_read_b128 v[150:153], v157 offset:20064
	s_waitcnt lgkmcnt(2)
	v_mfma_f32_32x32x16_bf16 v[48:63], v[162:165], v[104:107], v[48:63]
	s_waitcnt lgkmcnt(1)
	v_mfma_f32_32x32x16_bf16 v[64:79], v[146:149], v[108:111], v[64:79]
	ds_read_b128 v[168:171], v157 offset:13440
	ds_read_b128 v[162:165], v157 offset:20096
	s_waitcnt lgkmcnt(2)
	v_mfma_f32_32x32x16_bf16 v[48:63], v[150:153], v[108:111], v[48:63]
	s_waitcnt lgkmcnt(1)
	v_mfma_f32_32x32x16_bf16 v[64:79], v[168:171], v[112:115], v[64:79]
	ds_read_b128 v[150:153], v157 offset:13472
	ds_read_b128 v[172:175], v157 offset:20128
	ds_read_b64_tr_b16 v[168:169], v199 offset:0
	ds_read_b64_tr_b16 v[170:171], v199 offset:0x100
	s_waitcnt lgkmcnt(4)
	v_mfma_f32_32x32x16_bf16 v[48:63], v[162:165], v[112:115], v[48:63]
	ds_read_b64_tr_b16 v[146:147], v199 offset:0x800
	ds_read_b64_tr_b16 v[148:149], v199 offset:0x900
	ds_read_b64_tr_b16 v[182:183], v199 offset:0x1000
	ds_read_b64_tr_b16 v[184:185], v199 offset:0x1100
	ds_read_b64_tr_b16 v[186:187], v199 offset:0x1800
	ds_read_b64_tr_b16 v[188:189], v199 offset:0x1900
	ds_read_b64_tr_b16 v[190:191], v199 offset:0x200
	ds_read_b64_tr_b16 v[192:193], v199 offset:0x300
	s_waitcnt lgkmcnt(11)
	v_mfma_f32_32x32x16_bf16 v[64:79], v[150:153], v[116:119], v[64:79]
	ds_read_b64_tr_b16 v[150:151], v199 offset:0xa00
	ds_read_b64_tr_b16 v[152:153], v199 offset:0xb00
	ds_read_b64_tr_b16 v[208:209], v199 offset:0x1200
	ds_read_b64_tr_b16 v[210:211], v199 offset:0x1300
	ds_read_b64_tr_b16 v[212:213], v199 offset:0x1a00
	ds_read_b64_tr_b16 v[214:215], v199 offset:0x1b00
	s_waitcnt lgkmcnt(0)
	v_mfma_f32_32x32x16_bf16 v[48:63], v[172:175], v[116:119], v[48:63]
	v_mfma_f32_32x32x16_bf16 v[0:15], v[92:95], v[168:171], v[0:15]
	v_mfma_f32_32x32x16_bf16 v[0:15], v[88:91], v[146:149], v[0:15]
	v_mfma_f32_32x32x16_bf16 v[0:15], v[84:87], v[182:185], v[0:15]
	v_mfma_f32_32x32x16_bf16 v[0:15], v[80:83], v[186:189], v[0:15]
	s_waitcnt lgkmcnt(0)
	s_cmp_lg_u32 s40, 0
	s_cbranch_scc0 .Lmla_nobar6
	s_barrier
.Lmla_nobar6:
	v_mfma_f32_32x32x16_bf16 v[16:31], v[92:95], v[190:193], v[16:31]
	v_mfma_f32_32x32x16_bf16 v[16:31], v[88:91], v[150:153], v[16:31]
	s_cmp_lt_i32 s47, s54
	s_cbranch_scc0 .Lmla_w2_tail
	s_waitcnt vmcnt(3)
	ds_write_b128 v200, v[136:139]
	ds_write_b128 v201, v[132:135] offset:26624
	s_cmp_lg_u32 s8, 0
	s_cbranch_scc0 .LBB0_991
	ds_write_b128 v239, v[140:143] offset:128
.LBB0_991:
	v_mfma_f32_32x32x16_bf16 v[16:31], v[84:87], v[208:211], v[16:31]
	v_mfma_f32_32x32x16_bf16 v[16:31], v[80:83], v[212:215], v[16:31]
	v_exp_f32_e32 v218, v64
	v_exp_f32_e32 v219, v65
	v_exp_f32_e32 v220, v66
	v_exp_f32_e32 v221, v67
	v_add_f32_e32 v173, v218, v220
	v_exp_f32_e32 v222, v68
	v_add_f32_e32 v174, v219, v221
	v_exp_f32_e32 v223, v69
	v_add_f32_e32 v173, v222, v173
	v_exp_f32_e32 v224, v70
	v_add_f32_e32 v174, v223, v174
	v_exp_f32_e32 v225, v71
	v_add_f32_e32 v173, v224, v173
	v_exp_f32_e32 v226, v72
	v_add_f32_e32 v174, v225, v174
	v_exp_f32_e32 v227, v73
	v_add_f32_e32 v173, v226, v173
	v_exp_f32_e32 v228, v74
	v_add_f32_e32 v174, v227, v174
	v_exp_f32_e32 v229, v75
	v_add_f32_e32 v173, v228, v173
	v_exp_f32_e32 v230, v76
	v_add_f32_e32 v174, v229, v174
	v_exp_f32_e32 v231, v77
	v_add_f32_e32 v173, v230, v173
	v_exp_f32_e32 v232, v78
	v_add_f32_e32 v174, v231, v174
	v_exp_f32_e32 v233, v79
	v_add_f32_e32 v173, v232, v173
	v_exp_f32_e32 v234, v48
	v_add_f32_e32 v174, v233, v174
	v_exp_f32_e32 v240, v49
	v_add_f32_e32 v173, v234, v173
	v_exp_f32_e32 v241, v50
	v_add_f32_e32 v174, v240, v174
	v_exp_f32_e32 v242, v51
	v_add_f32_e32 v173, v241, v173
	v_exp_f32_e32 v243, v52
	v_add_f32_e32 v174, v242, v174
	v_exp_f32_e32 v244, v53
	v_add_f32_e32 v173, v243, v173
	v_exp_f32_e32 v245, v54
	v_add_f32_e32 v174, v244, v174
	v_exp_f32_e32 v246, v55
	v_add_f32_e32 v173, v245, v173
	v_exp_f32_e32 v247, v56
	v_add_f32_e32 v174, v246, v174
	v_exp_f32_e32 v248, v57
	v_add_f32_e32 v173, v247, v173
	v_exp_f32_e32 v249, v58
	v_add_f32_e32 v174, v248, v174
	v_exp_f32_e32 v250, v59
	v_add_f32_e32 v173, v249, v173
	v_exp_f32_e32 v251, v60
	v_add_f32_e32 v174, v250, v174
	v_exp_f32_e32 v252, v61
	v_add_f32_e32 v173, v251, v173
	v_exp_f32_e32 v253, v62
	v_add_f32_e32 v174, v252, v174
	v_exp_f32_e32 v172, v63
	v_add_f32_e32 v173, v253, v173
	v_add_f32_e32 v174, v172, v174
	v_add_f32_e32 v173, v173, v174
	v_cmp_ge_f32_e32 vcc, 0x47800000, v173
	s_cmp_eq_u64 vcc, exec
	s_cbranch_scc0 .LBB0_996
	v_add_f32_e32 v236, v236, v173

.Lmla_w1_tail:
	s_cmp_ge_i32 s47, s55
	s_cbranch_scc1 .LBB0_973
	s_waitcnt vmcnt(1)
	ds_write_b128 v196, v[120:123]
	s_and_saveexec_b64 s[12:13], s[8:9]
	s_cbranch_execz .LBB0_972
	v_add_u32_e32 v180, v155, v156
	s_waitcnt vmcnt(0)
	ds_write_b128 v180, v[124:127] offset:128

.Lmla_w2_tail:
	s_and_b64 vcc, exec, s[12:13]
	s_cbranch_vccnz .LBB0_989
	s_waitcnt vmcnt(1)
	ds_write_b128 v200, v[136:139]
	s_and_saveexec_b64 s[12:13], s[8:9]
	s_cbranch_execz .LBB0_988
	v_add_u32_e32 v180, v198, v156
	s_waitcnt vmcnt(0)
	ds_write_b128 v180, v[140:143] offset:128
